# v7 + the six GEMM K-loop heads aligned to 64 bytes (p2align 6 before each loop label)
# baseline (speedup 1.0000x reference)
; template <class Epi, class Sched, bool ALIGN_EPI = false, bool SP2 = false>
; __device__ __forceinline__ void gemm_phase(PG8_LAS unsigned char* lds, const Gemm g, const Sched& S, const Epi& E, const int wave_id) {
;     ...
;         const bool has_next = S.next(ui + 1, nxt);
;         const char* nA = has_next ? (const char*)g.A + (size_t)nxt.pm * tstep : cA; const char* nB = has_next ? (const char*)g.Bt + (size_t)nxt.pn * tstep : cB;
;         for (int t = 0; t < nt; t += 2) {
;             const bool last = (t == nt - 2);
;             const char* a1 = cA + (size_t)(t + 1) * kstep;
;             const char* a2 = last ? nA : cA + (size_t)(t + 2) * kstep; const char* b2 = last ? nB : cB + (size_t)(t + 2) * kstep;
;             const char* a3 = a2 + kstep; const char* b3 = b2 + kstep;
;     ...
; #pragma unroll
;         for (int a = 0; a < 2; ++a)
; #pragma unroll
;             for (int b = 0; b < 2; ++b)
; #pragma unroll
;                 for (int m = 0; m < 4; ++m)
; #pragma unroll
;                     for (int n = 0; n < 2; ++n) acc[a][b][m][n] = (f32x4){0.f, 0.f, 0.f, 0.f};
.LBB0_389:
	s_ashr_i32 s23, s22, 31
	s_lshl_b64 s[24:25], s[22:23], 19
	s_add_u32 s24, s44, s24
	s_addc_u32 s25, s45, s25
	s_and_b64 s[26:27], s[4:5], exec
	s_cselect_b32 s23, s25, s31
	s_cselect_b32 s59, s24, s30
	s_ashr_i32 s21, s20, 31
	s_lshl_b64 s[26:27], s[20:21], 19
	s_add_u32 s26, s46, s26
	s_addc_u32 s27, s47, s27
	s_and_b64 s[36:37], s[4:5], exec
	s_cselect_b32 s21, s27, s35
	s_cselect_b32 s60, s26, s34
	s_add_u32 s30, s30, 0x40080
	s_addc_u32 s31, s31, 0
	s_add_u32 s61, s34, 0x100
	v_mov_b32_e32 v0, 0
	s_addc_u32 s62, s35, 0
	s_mov_b32 s63, -2
	v_mov_b32_e32 v1, v0
	v_mov_b32_e32 v2, v0
	v_mov_b32_e32 v3, v0
	v_mov_b32_e32 v4, v0
	v_mov_b32_e32 v5, v0
	v_mov_b32_e32 v6, v0
	v_mov_b32_e32 v7, v0
	v_mov_b32_e32 v16, v0
	v_mov_b32_e32 v17, v0
	v_mov_b32_e32 v18, v0
	v_mov_b32_e32 v19, v0
	v_mov_b32_e32 v20, v0
	v_mov_b32_e32 v21, v0
	v_mov_b32_e32 v22, v0
	v_mov_b32_e32 v23, v0
	v_mov_b32_e32 v32, v0
	v_mov_b32_e32 v33, v0
	v_mov_b32_e32 v34, v0
	v_mov_b32_e32 v35, v0
	v_mov_b32_e32 v36, v0
	v_mov_b32_e32 v37, v0
	v_mov_b32_e32 v38, v0
	v_mov_b32_e32 v39, v0
	v_mov_b32_e32 v48, v0
	v_mov_b32_e32 v49, v0
	v_mov_b32_e32 v50, v0
	v_mov_b32_e32 v51, v0
	v_mov_b32_e32 v52, v0
	v_mov_b32_e32 v53, v0
	v_mov_b32_e32 v54, v0
	v_mov_b32_e32 v55, v0
	v_mov_b32_e32 v8, v0
	v_mov_b32_e32 v9, v0
	v_mov_b32_e32 v10, v0
	v_mov_b32_e32 v11, v0
	v_mov_b32_e32 v12, v0
	v_mov_b32_e32 v13, v0
	v_mov_b32_e32 v14, v0
	v_mov_b32_e32 v15, v0
	v_mov_b32_e32 v24, v0
	v_mov_b32_e32 v25, v0
	v_mov_b32_e32 v26, v0
	v_mov_b32_e32 v27, v0
	v_mov_b32_e32 v28, v0
	v_mov_b32_e32 v29, v0
	v_mov_b32_e32 v30, v0
	v_mov_b32_e32 v31, v0
	v_mov_b32_e32 v40, v0
	v_mov_b32_e32 v41, v0
	v_mov_b32_e32 v42, v0
	v_mov_b32_e32 v43, v0
	v_mov_b32_e32 v44, v0
	v_mov_b32_e32 v45, v0
	v_mov_b32_e32 v46, v0
	v_mov_b32_e32 v47, v0
	v_mov_b32_e32 v56, v0
	v_mov_b32_e32 v57, v0
	v_mov_b32_e32 v58, v0
	v_mov_b32_e32 v59, v0
	v_mov_b32_e32 v60, v0
	v_mov_b32_e32 v61, v0
	v_mov_b32_e32 v62, v0
	v_mov_b32_e32 v63, v0
	v_mov_b32_e32 v64, v0
	v_mov_b32_e32 v65, v0
	v_mov_b32_e32 v66, v0
	v_mov_b32_e32 v67, v0
	v_mov_b32_e32 v68, v0
	v_mov_b32_e32 v69, v0
	v_mov_b32_e32 v70, v0
	v_mov_b32_e32 v71, v0
	v_mov_b32_e32 v80, v0
	v_mov_b32_e32 v81, v0
	v_mov_b32_e32 v82, v0
	v_mov_b32_e32 v83, v0
	v_mov_b32_e32 v84, v0
	v_mov_b32_e32 v85, v0
	v_mov_b32_e32 v86, v0
	v_mov_b32_e32 v87, v0
	v_mov_b32_e32 v96, v0
	v_mov_b32_e32 v97, v0
	v_mov_b32_e32 v98, v0
	v_mov_b32_e32 v99, v0
	v_mov_b32_e32 v100, v0
	v_mov_b32_e32 v101, v0
	v_mov_b32_e32 v102, v0
	v_mov_b32_e32 v103, v0
	v_mov_b32_e32 v112, v0
	v_mov_b32_e32 v113, v0
	v_mov_b32_e32 v114, v0
	v_mov_b32_e32 v115, v0
	v_mov_b32_e32 v116, v0
	v_mov_b32_e32 v117, v0
	v_mov_b32_e32 v118, v0
	v_mov_b32_e32 v119, v0
	v_mov_b32_e32 v72, v0
	v_mov_b32_e32 v73, v0
	v_mov_b32_e32 v74, v0
	v_mov_b32_e32 v75, v0
	v_mov_b32_e32 v76, v0
	v_mov_b32_e32 v77, v0
	v_mov_b32_e32 v78, v0
	v_mov_b32_e32 v79, v0
	v_mov_b32_e32 v88, v0
	v_mov_b32_e32 v89, v0
	v_mov_b32_e32 v90, v0
	v_mov_b32_e32 v91, v0
	v_mov_b32_e32 v92, v0
	v_mov_b32_e32 v93, v0
	v_mov_b32_e32 v94, v0
	v_mov_b32_e32 v95, v0
	v_mov_b32_e32 v104, v0
	v_mov_b32_e32 v105, v0
	v_mov_b32_e32 v106, v0
	v_mov_b32_e32 v107, v0
	v_mov_b32_e32 v108, v0
	v_mov_b32_e32 v109, v0
	v_mov_b32_e32 v110, v0
	v_mov_b32_e32 v111, v0
	v_mov_b32_e32 v120, v0
	v_mov_b32_e32 v121, v0
	v_mov_b32_e32 v122, v0
	v_mov_b32_e32 v123, v0
	v_mov_b32_e32 v124, v0
	v_mov_b32_e32 v125, v0
	v_mov_b32_e32 v126, v0
	v_mov_b32_e32 v127, v0
	.p2align 6

; template <class Epi, class Sched, bool ALIGN_EPI = false, bool SP2 = false>
; __device__ __forceinline__ void gemm_phase(PG8_LAS unsigned char* lds, const Gemm g, const Sched& S, const Epi& E, const int wave_id) {
;     ...
;         const bool has_next = S.next(ui + 1, nxt);
;         const char* nA = has_next ? (const char*)g.A + (size_t)nxt.pm * tstep : cA; const char* nB = has_next ? (const char*)g.Bt + (size_t)nxt.pn * tstep : cB;
;         for (int t = 0; t < nt; t += 2) {
;             const bool last = (t == nt - 2);
;             const char* a1 = cA + (size_t)(t + 1) * kstep;
;             const char* a2 = last ? nA : cA + (size_t)(t + 2) * kstep; const char* b2 = last ? nB : cB + (size_t)(t + 2) * kstep;
;             const char* a3 = a2 + kstep; const char* b3 = b2 + kstep;
;     ...
; #pragma unroll
;         for (int a = 0; a < 2; ++a)
; #pragma unroll
;             for (int b = 0; b < 2; ++b)
; #pragma unroll
;                 for (int m = 0; m < 4; ++m)
; #pragma unroll
;                     for (int n = 0; n < 2; ++n) acc[a][b][m][n] = (f32x4){0.f, 0.f, 0.f, 0.f};
.LBB0_694:
	s_ashr_i32 s61, s60, 31
	s_lshl_b64 s[16:17], s[60:61], 19
	s_add_u32 s62, s80, s16
	s_addc_u32 s63, s83, s17
	s_and_b64 s[16:17], s[8:9], exec
	s_cselect_b32 s11, s63, s13
	s_cselect_b32 s61, s62, s12
	s_ashr_i32 s59, s58, 31
	s_lshl_b64 s[16:17], s[58:59], 19
	s_add_u32 s64, s22, s16
	s_addc_u32 s65, s23, s17
	s_and_b64 s[16:17], s[8:9], exec
	s_cselect_b32 s59, s65, s15
	s_cselect_b32 s67, s64, s14
	s_add_u32 s12, s12, 0x40080
	s_addc_u32 s13, s13, 0
	s_add_u32 s68, s14, 0x100
	v_mov_b32_e32 v0, 0
	s_addc_u32 s69, s15, 0
	s_mov_b32 s72, -2
	v_mov_b32_e32 v1, v0
	v_mov_b32_e32 v2, v0
	v_mov_b32_e32 v3, v0
	v_mov_b32_e32 v4, v0
	v_mov_b32_e32 v5, v0
	v_mov_b32_e32 v6, v0
	v_mov_b32_e32 v7, v0
	v_mov_b32_e32 v8, v0
	v_mov_b32_e32 v9, v0
	v_mov_b32_e32 v10, v0
	v_mov_b32_e32 v11, v0
	v_mov_b32_e32 v12, v0
	v_mov_b32_e32 v13, v0
	v_mov_b32_e32 v14, v0
	v_mov_b32_e32 v15, v0
	v_mov_b32_e32 v16, v0
	v_mov_b32_e32 v17, v0
	v_mov_b32_e32 v18, v0
	v_mov_b32_e32 v19, v0
	v_mov_b32_e32 v20, v0
	v_mov_b32_e32 v21, v0
	v_mov_b32_e32 v22, v0
	v_mov_b32_e32 v23, v0
	v_mov_b32_e32 v24, v0
	v_mov_b32_e32 v25, v0
	v_mov_b32_e32 v26, v0
	v_mov_b32_e32 v27, v0
	v_mov_b32_e32 v28, v0
	v_mov_b32_e32 v29, v0
	v_mov_b32_e32 v30, v0
	v_mov_b32_e32 v31, v0
	v_mov_b32_e32 v68, v0
	v_mov_b32_e32 v69, v0
	v_mov_b32_e32 v70, v0
	v_mov_b32_e32 v71, v0
	v_mov_b32_e32 v84, v0
	v_mov_b32_e32 v85, v0
	v_mov_b32_e32 v86, v0
	v_mov_b32_e32 v87, v0
	v_mov_b32_e32 v72, v0
	v_mov_b32_e32 v73, v0
	v_mov_b32_e32 v74, v0
	v_mov_b32_e32 v75, v0
	v_mov_b32_e32 v92, v0
	v_mov_b32_e32 v93, v0
	v_mov_b32_e32 v94, v0
	v_mov_b32_e32 v95, v0
	v_mov_b32_e32 v88, v0
	v_mov_b32_e32 v89, v0
	v_mov_b32_e32 v90, v0
	v_mov_b32_e32 v91, v0
	v_mov_b32_e32 v100, v0
	v_mov_b32_e32 v101, v0
	v_mov_b32_e32 v102, v0
	v_mov_b32_e32 v103, v0
	v_mov_b32_e32 v96, v0
	v_mov_b32_e32 v97, v0
	v_mov_b32_e32 v98, v0
	v_mov_b32_e32 v99, v0
	v_mov_b32_e32 v108, v0
	v_mov_b32_e32 v109, v0
	v_mov_b32_e32 v110, v0
	v_mov_b32_e32 v111, v0
	v_mov_b32_e32 v44, v0
	v_mov_b32_e32 v45, v0
	v_mov_b32_e32 v46, v0
	v_mov_b32_e32 v47, v0
	v_mov_b32_e32 v48, v0
	v_mov_b32_e32 v49, v0
	v_mov_b32_e32 v50, v0
	v_mov_b32_e32 v51, v0
	v_mov_b32_e32 v52, v0
	v_mov_b32_e32 v53, v0
	v_mov_b32_e32 v54, v0
	v_mov_b32_e32 v55, v0
	v_mov_b32_e32 v56, v0
	v_mov_b32_e32 v57, v0
	v_mov_b32_e32 v58, v0
	v_mov_b32_e32 v59, v0
	v_mov_b32_e32 v60, v0
	v_mov_b32_e32 v61, v0
	v_mov_b32_e32 v62, v0
	v_mov_b32_e32 v63, v0
	v_mov_b32_e32 v64, v0
	v_mov_b32_e32 v65, v0
	v_mov_b32_e32 v66, v0
	v_mov_b32_e32 v67, v0
	v_mov_b32_e32 v76, v0
	v_mov_b32_e32 v77, v0
	v_mov_b32_e32 v78, v0
	v_mov_b32_e32 v79, v0
	v_mov_b32_e32 v80, v0
	v_mov_b32_e32 v81, v0
	v_mov_b32_e32 v82, v0
	v_mov_b32_e32 v83, v0
	v_mov_b32_e32 v104, v0
	v_mov_b32_e32 v105, v0
	v_mov_b32_e32 v106, v0
	v_mov_b32_e32 v107, v0
	v_mov_b32_e32 v112, v0
	v_mov_b32_e32 v113, v0
	v_mov_b32_e32 v114, v0
	v_mov_b32_e32 v115, v0
	v_mov_b32_e32 v116, v0
	v_mov_b32_e32 v117, v0
	v_mov_b32_e32 v118, v0
	v_mov_b32_e32 v119, v0
	v_mov_b32_e32 v120, v0
	v_mov_b32_e32 v121, v0
	v_mov_b32_e32 v122, v0
	v_mov_b32_e32 v123, v0
	v_mov_b32_e32 v124, v0
	v_mov_b32_e32 v125, v0
	v_mov_b32_e32 v126, v0
	v_mov_b32_e32 v127, v0
	v_mov_b32_e32 v128, v0
	v_mov_b32_e32 v129, v0
	v_mov_b32_e32 v130, v0
	v_mov_b32_e32 v131, v0
	v_mov_b32_e32 v132, v0
	v_mov_b32_e32 v133, v0
	v_mov_b32_e32 v134, v0
	v_mov_b32_e32 v135, v0
	v_mov_b32_e32 v136, v0
	v_mov_b32_e32 v137, v0
	v_mov_b32_e32 v138, v0
	v_mov_b32_e32 v139, v0
	.p2align 6

; template <class Epi, class Sched, bool ALIGN_EPI = false, bool SP2 = false>
; __device__ __forceinline__ void gemm_phase(PG8_LAS unsigned char* lds, const Gemm g, const Sched& S, const Epi& E, const int wave_id) {
;     ...
;         const bool has_next = S.next(ui + 1, nxt);
;         const char* nA = has_next ? (const char*)g.A + (size_t)nxt.pm * tstep : cA; const char* nB = has_next ? (const char*)g.Bt + (size_t)nxt.pn * tstep : cB;
;         for (int t = 0; t < nt; t += 2) {
;             const bool last = (t == nt - 2);
;             const char* a1 = cA + (size_t)(t + 1) * kstep;
;             const char* a2 = last ? nA : cA + (size_t)(t + 2) * kstep; const char* b2 = last ? nB : cB + (size_t)(t + 2) * kstep;
;             const char* a3 = a2 + kstep; const char* b3 = b2 + kstep;
;     ...
; #pragma unroll
;         for (int a = 0; a < 2; ++a)
; #pragma unroll
;             for (int b = 0; b < 2; ++b)
; #pragma unroll
;                 for (int m = 0; m < 4; ++m)
; #pragma unroll
;                     for (int n = 0; n < 2; ++n) acc[a][b][m][n] = (f32x4){0.f, 0.f, 0.f, 0.f};
.LBB0_1026:
	s_ashr_i32 s43, s42, 31
	s_lshl_b64 s[0:1], s[42:43], 19
	s_add_u32 s44, s65, s0
	s_addc_u32 s45, s66, s1
	s_and_b64 s[0:1], s[6:7], exec
	s_cselect_b32 s0, s45, s13
	s_cselect_b32 s1, s44, s12
	s_ashr_i32 s41, s40, 31
	s_lshl_b64 s[16:17], s[40:41], 19
	s_add_u32 s46, s20, s16
	s_addc_u32 s47, s21, s17
	s_and_b64 s[16:17], s[6:7], exec
	s_cselect_b32 s9, s47, s15
	s_cselect_b32 s11, s46, s14
	s_add_u32 s12, s12, 0x40080
	s_addc_u32 s13, s13, 0
	s_add_u32 s41, s14, 0x100
	v_mov_b32_e32 v0, 0
	s_addc_u32 s43, s15, 0
	s_mov_b32 s48, -2
	v_mov_b32_e32 v1, v0
	v_mov_b32_e32 v2, v0
	v_mov_b32_e32 v3, v0
	v_mov_b32_e32 v4, v0
	v_mov_b32_e32 v5, v0
	v_mov_b32_e32 v6, v0
	v_mov_b32_e32 v7, v0
	v_mov_b32_e32 v16, v0
	v_mov_b32_e32 v17, v0
	v_mov_b32_e32 v18, v0
	v_mov_b32_e32 v19, v0
	v_mov_b32_e32 v20, v0
	v_mov_b32_e32 v21, v0
	v_mov_b32_e32 v22, v0
	v_mov_b32_e32 v23, v0
	v_mov_b32_e32 v32, v0
	v_mov_b32_e32 v33, v0
	v_mov_b32_e32 v34, v0
	v_mov_b32_e32 v35, v0
	v_mov_b32_e32 v36, v0
	v_mov_b32_e32 v37, v0
	v_mov_b32_e32 v38, v0
	v_mov_b32_e32 v39, v0
	v_mov_b32_e32 v48, v0
	v_mov_b32_e32 v49, v0
	v_mov_b32_e32 v50, v0
	v_mov_b32_e32 v51, v0
	v_mov_b32_e32 v52, v0
	v_mov_b32_e32 v53, v0
	v_mov_b32_e32 v54, v0
	v_mov_b32_e32 v55, v0
	v_mov_b32_e32 v8, v0
	v_mov_b32_e32 v9, v0
	v_mov_b32_e32 v10, v0
	v_mov_b32_e32 v11, v0
	v_mov_b32_e32 v12, v0
	v_mov_b32_e32 v13, v0
	v_mov_b32_e32 v14, v0
	v_mov_b32_e32 v15, v0
	v_mov_b32_e32 v24, v0
	v_mov_b32_e32 v25, v0
	v_mov_b32_e32 v26, v0
	v_mov_b32_e32 v27, v0
	v_mov_b32_e32 v28, v0
	v_mov_b32_e32 v29, v0
	v_mov_b32_e32 v30, v0
	v_mov_b32_e32 v31, v0
	v_mov_b32_e32 v40, v0
	v_mov_b32_e32 v41, v0
	v_mov_b32_e32 v42, v0
	v_mov_b32_e32 v43, v0
	v_mov_b32_e32 v44, v0
	v_mov_b32_e32 v45, v0
	v_mov_b32_e32 v46, v0
	v_mov_b32_e32 v47, v0
	v_mov_b32_e32 v56, v0
	v_mov_b32_e32 v57, v0
	v_mov_b32_e32 v58, v0
	v_mov_b32_e32 v59, v0
	v_mov_b32_e32 v60, v0
	v_mov_b32_e32 v61, v0
	v_mov_b32_e32 v62, v0
	v_mov_b32_e32 v63, v0
	v_mov_b32_e32 v64, v0
	v_mov_b32_e32 v65, v0
	v_mov_b32_e32 v66, v0
	v_mov_b32_e32 v67, v0
	v_mov_b32_e32 v68, v0
	v_mov_b32_e32 v69, v0
	v_mov_b32_e32 v70, v0
	v_mov_b32_e32 v71, v0
	v_mov_b32_e32 v80, v0
	v_mov_b32_e32 v81, v0
	v_mov_b32_e32 v82, v0
	v_mov_b32_e32 v83, v0
	v_mov_b32_e32 v84, v0
	v_mov_b32_e32 v85, v0
	v_mov_b32_e32 v86, v0
	v_mov_b32_e32 v87, v0
	v_mov_b32_e32 v96, v0
	v_mov_b32_e32 v97, v0
	v_mov_b32_e32 v98, v0
	v_mov_b32_e32 v99, v0
	v_mov_b32_e32 v100, v0
	v_mov_b32_e32 v101, v0
	v_mov_b32_e32 v102, v0
	v_mov_b32_e32 v103, v0
	v_mov_b32_e32 v112, v0
	v_mov_b32_e32 v113, v0
	v_mov_b32_e32 v114, v0
	v_mov_b32_e32 v115, v0
	v_mov_b32_e32 v116, v0
	v_mov_b32_e32 v117, v0
	v_mov_b32_e32 v118, v0
	v_mov_b32_e32 v119, v0
	v_mov_b32_e32 v72, v0
	v_mov_b32_e32 v73, v0
	v_mov_b32_e32 v74, v0
	v_mov_b32_e32 v75, v0
	v_mov_b32_e32 v76, v0
	v_mov_b32_e32 v77, v0
	v_mov_b32_e32 v78, v0
	v_mov_b32_e32 v79, v0
	v_mov_b32_e32 v88, v0
	v_mov_b32_e32 v89, v0
	v_mov_b32_e32 v90, v0
	v_mov_b32_e32 v91, v0
	v_mov_b32_e32 v92, v0
	v_mov_b32_e32 v93, v0
	v_mov_b32_e32 v94, v0
	v_mov_b32_e32 v95, v0
	v_mov_b32_e32 v104, v0
	v_mov_b32_e32 v105, v0
	v_mov_b32_e32 v106, v0
	v_mov_b32_e32 v107, v0
	v_mov_b32_e32 v108, v0
	v_mov_b32_e32 v109, v0
	v_mov_b32_e32 v110, v0
	v_mov_b32_e32 v111, v0
	v_mov_b32_e32 v120, v0
	v_mov_b32_e32 v121, v0
	v_mov_b32_e32 v122, v0
	v_mov_b32_e32 v123, v0
	v_mov_b32_e32 v124, v0
	v_mov_b32_e32 v125, v0
	v_mov_b32_e32 v126, v0
	v_mov_b32_e32 v127, v0
	.p2align 6

; template <class Epi, class Sched, bool ALIGN_EPI = false, bool SP2 = false>
; __device__ __forceinline__ void gemm_phase(PG8_LAS unsigned char* lds, const Gemm g, const Sched& S, const Epi& E, const int wave_id) {
;     ...
;         const bool has_next = S.next(ui + 1, nxt);
;         const char* nA = has_next ? (const char*)g.A + (size_t)nxt.pm * tstep : cA; const char* nB = has_next ? (const char*)g.Bt + (size_t)nxt.pn * tstep : cB;
;         for (int t = 0; t < nt; t += 2) {
;             const bool last = (t == nt - 2);
;             const char* a1 = cA + (size_t)(t + 1) * kstep;
;             const char* a2 = last ? nA : cA + (size_t)(t + 2) * kstep; const char* b2 = last ? nB : cB + (size_t)(t + 2) * kstep;
;             const char* a3 = a2 + kstep; const char* b3 = b2 + kstep;
.LBB0_1717:
	s_ashr_i32 s23, s22, 31
	s_lshl_b64 s[24:25], s[22:23], 20
	s_add_u32 s24, s44, s24
	s_addc_u32 s25, s45, s25
	s_and_b64 s[26:27], s[4:5], exec
	s_cselect_b32 s23, s25, s37
	s_cselect_b32 s29, s24, s36
	s_ashr_i32 s21, s20, 31
	s_lshl_b64 s[26:27], s[20:21], 20
	s_add_u32 s26, s12, s26
	s_addc_u32 s27, s13, s27
	s_and_b64 s[38:39], s[4:5], exec
	s_cselect_b32 s21, s27, s35
	s_cselect_b32 s31, s26, s34
	s_add_u32 s36, s36, 0x80080
	s_addc_u32 s37, s37, 0
	s_add_u32 s60, s34, 0x100
	s_addc_u32 s61, s35, 0
	s_mov_b32 s62, -2
	.p2align 6

; template <class Epi, class Sched, bool ALIGN_EPI = false, bool SP2 = false>
; __device__ __forceinline__ void gemm_phase(PG8_LAS unsigned char* lds, const Gemm g, const Sched& S, const Epi& E, const int wave_id) {
;     ...
;         const bool has_next = S.next(ui + 1, nxt);
;         const char* nA = has_next ? (const char*)g.A + (size_t)nxt.pm * tstep : cA; const char* nB = has_next ? (const char*)g.Bt + (size_t)nxt.pn * tstep : cB;
;         for (int t = 0; t < nt; t += 2) {
;             const bool last = (t == nt - 2);
;             const char* a1 = cA + (size_t)(t + 1) * kstep;
;             const char* a2 = last ? nA : cA + (size_t)(t + 2) * kstep; const char* b2 = last ? nB : cB + (size_t)(t + 2) * kstep;
;             const char* a3 = a2 + kstep; const char* b3 = b2 + kstep;
;     ...
; #pragma unroll
;         for (int a = 0; a < 2; ++a)
; #pragma unroll
;             for (int b = 0; b < 2; ++b)
; #pragma unroll
;                 for (int m = 0; m < 4; ++m)
; #pragma unroll
;                     for (int n = 0; n < 2; ++n) acc[a][b][m][n] = (f32x4){0.f, 0.f, 0.f, 0.f};
.LBB0_1862:
	s_ashr_i32 s29, s28, 31
	s_lshl_b64 s[30:31], s[28:29], 19
	s_add_u32 s30, s49, s30
	s_addc_u32 s31, s50, s31
	s_and_b64 s[34:35], s[4:5], exec
	s_cselect_b32 s7, s31, s39
	s_cselect_b32 s29, s30, s38
	s_ashr_i32 s27, s26, 31
	s_lshl_b64 s[34:35], s[26:27], 19
	s_add_u32 s34, s14, s34
	s_addc_u32 s35, s15, s35
	s_and_b64 s[42:43], s[4:5], exec
	s_cselect_b32 s27, s35, s41
	s_cselect_b32 s37, s34, s40
	s_add_u32 s38, s38, 0x40080
	s_addc_u32 s39, s39, 0
	s_add_u32 s63, s40, 0x100
	v_mov_b32_e32 v0, 0
	s_addc_u32 s64, s41, 0
	s_mov_b32 s65, -2
	v_mov_b32_e32 v1, v0
	v_mov_b32_e32 v2, v0
	v_mov_b32_e32 v3, v0
	v_mov_b32_e32 v4, v0
	v_mov_b32_e32 v5, v0
	v_mov_b32_e32 v6, v0
	v_mov_b32_e32 v7, v0
	v_mov_b32_e32 v16, v0
	v_mov_b32_e32 v17, v0
	v_mov_b32_e32 v18, v0
	v_mov_b32_e32 v19, v0
	v_mov_b32_e32 v20, v0
	v_mov_b32_e32 v21, v0
	v_mov_b32_e32 v22, v0
	v_mov_b32_e32 v23, v0
	v_mov_b32_e32 v32, v0
	v_mov_b32_e32 v33, v0
	v_mov_b32_e32 v34, v0
	v_mov_b32_e32 v35, v0
	v_mov_b32_e32 v36, v0
	v_mov_b32_e32 v37, v0
	v_mov_b32_e32 v38, v0
	v_mov_b32_e32 v39, v0
	v_mov_b32_e32 v48, v0
	v_mov_b32_e32 v49, v0
	v_mov_b32_e32 v50, v0
	v_mov_b32_e32 v51, v0
	v_mov_b32_e32 v52, v0
	v_mov_b32_e32 v53, v0
	v_mov_b32_e32 v54, v0
	v_mov_b32_e32 v55, v0
	v_mov_b32_e32 v8, v0
	v_mov_b32_e32 v9, v0
	v_mov_b32_e32 v10, v0
	v_mov_b32_e32 v11, v0
	v_mov_b32_e32 v12, v0
	v_mov_b32_e32 v13, v0
	v_mov_b32_e32 v14, v0
	v_mov_b32_e32 v15, v0
	v_mov_b32_e32 v24, v0
	v_mov_b32_e32 v25, v0
	v_mov_b32_e32 v26, v0
	v_mov_b32_e32 v27, v0
	v_mov_b32_e32 v28, v0
	v_mov_b32_e32 v29, v0
	v_mov_b32_e32 v30, v0
	v_mov_b32_e32 v31, v0
	v_mov_b32_e32 v40, v0
	v_mov_b32_e32 v41, v0
	v_mov_b32_e32 v42, v0
	v_mov_b32_e32 v43, v0
	v_mov_b32_e32 v44, v0
	v_mov_b32_e32 v45, v0
	v_mov_b32_e32 v46, v0
	v_mov_b32_e32 v47, v0
	v_mov_b32_e32 v56, v0
	v_mov_b32_e32 v57, v0
	v_mov_b32_e32 v58, v0
	v_mov_b32_e32 v59, v0
	v_mov_b32_e32 v60, v0
	v_mov_b32_e32 v61, v0
	v_mov_b32_e32 v62, v0
	v_mov_b32_e32 v63, v0
	v_mov_b32_e32 v64, v0
	v_mov_b32_e32 v65, v0
	v_mov_b32_e32 v66, v0
	v_mov_b32_e32 v67, v0
	v_mov_b32_e32 v68, v0
	v_mov_b32_e32 v69, v0
	v_mov_b32_e32 v70, v0
	v_mov_b32_e32 v71, v0
	v_mov_b32_e32 v80, v0
	v_mov_b32_e32 v81, v0
	v_mov_b32_e32 v82, v0
	v_mov_b32_e32 v83, v0
	v_mov_b32_e32 v84, v0
	v_mov_b32_e32 v85, v0
	v_mov_b32_e32 v86, v0
	v_mov_b32_e32 v87, v0
	v_mov_b32_e32 v96, v0
	v_mov_b32_e32 v97, v0
	v_mov_b32_e32 v98, v0
	v_mov_b32_e32 v99, v0
	v_mov_b32_e32 v100, v0
	v_mov_b32_e32 v101, v0
	v_mov_b32_e32 v102, v0
	v_mov_b32_e32 v103, v0
	v_mov_b32_e32 v112, v0
	v_mov_b32_e32 v113, v0
	v_mov_b32_e32 v114, v0
	v_mov_b32_e32 v115, v0
	v_mov_b32_e32 v116, v0
	v_mov_b32_e32 v117, v0
	v_mov_b32_e32 v118, v0
	v_mov_b32_e32 v119, v0
	v_mov_b32_e32 v72, v0
	v_mov_b32_e32 v73, v0
	v_mov_b32_e32 v74, v0
	v_mov_b32_e32 v75, v0
	v_mov_b32_e32 v76, v0
	v_mov_b32_e32 v77, v0
	v_mov_b32_e32 v78, v0
	v_mov_b32_e32 v79, v0
	v_mov_b32_e32 v88, v0
	v_mov_b32_e32 v89, v0
	v_mov_b32_e32 v90, v0
	v_mov_b32_e32 v91, v0
	v_mov_b32_e32 v92, v0
	v_mov_b32_e32 v93, v0
	v_mov_b32_e32 v94, v0
	v_mov_b32_e32 v95, v0
	v_mov_b32_e32 v104, v0
	v_mov_b32_e32 v105, v0
	v_mov_b32_e32 v106, v0
	v_mov_b32_e32 v107, v0
	v_mov_b32_e32 v108, v0
	v_mov_b32_e32 v109, v0
	v_mov_b32_e32 v110, v0
	v_mov_b32_e32 v111, v0
	v_mov_b32_e32 v120, v0
	v_mov_b32_e32 v121, v0
	v_mov_b32_e32 v122, v0
	v_mov_b32_e32 v123, v0
	v_mov_b32_e32 v124, v0
	v_mov_b32_e32 v125, v0
	v_mov_b32_e32 v126, v0
	v_mov_b32_e32 v127, v0
	.p2align 6

; template <class Epi, class Sched, bool ALIGN_EPI = false, bool SP2 = false>
; __device__ __forceinline__ void gemm_phase(PG8_LAS unsigned char* lds, const Gemm g, const Sched& S, const Epi& E, const int wave_id) {
;     ...
;         const bool has_next = S.next(ui + 1, nxt);
;         const char* nA = has_next ? (const char*)g.A + (size_t)nxt.pm * tstep : cA; const char* nB = has_next ? (const char*)g.Bt + (size_t)nxt.pn * tstep : cB;
;         for (int t = 0; t < nt; t += 2) {
;             const bool last = (t == nt - 2);
;             const char* a1 = cA + (size_t)(t + 1) * kstep;
;             const char* a2 = last ? nA : cA + (size_t)(t + 2) * kstep; const char* b2 = last ? nB : cB + (size_t)(t + 2) * kstep;
;             const char* a3 = a2 + kstep; const char* b3 = b2 + kstep;
.LBB0_2236:
	s_ashr_i32 s23, s22, 31
	s_lshl_b64 s[24:25], s[22:23], 19
	s_add_u32 s24, s44, s24
	s_addc_u32 s25, s45, s25
	s_and_b64 s[26:27], s[4:5], exec
	s_cselect_b32 s23, s25, s37
	s_cselect_b32 s29, s24, s36
	s_ashr_i32 s21, s20, 31
	s_lshl_b64 s[26:27], s[20:21], 19
	s_add_u32 s26, s12, s26
	s_addc_u32 s27, s13, s27
	s_and_b64 s[38:39], s[4:5], exec
	s_cselect_b32 s21, s27, s35
	s_cselect_b32 s31, s26, s34
	s_add_u32 s36, s36, 0x40080
	s_addc_u32 s37, s37, 0
	s_add_u32 s60, s34, 0x100
	s_addc_u32 s61, s35, 0
	s_mov_b32 s62, -2
	.p2align 6
